# attention unit polish: first PV V-fragments prefetched under softmax (replaces nop padding), epilogue packs two outputs per cvt + d16_hi stores
# baseline (speedup 1.0000x reference)
.Lam_loop:
	ds_read_b128 v[212:215], v228 offset:0
	ds_read_b128 v[216:219], v228 offset:8192
	ds_read_b128 v[220:223], v229 offset:0
	ds_read_b128 v[224:227], v229 offset:8192
	s_waitcnt lgkmcnt(2)
	v_mfma_f32_32x32x16_bf16 v[162:177], v[212:215], v[130:133], 0
	v_mfma_f32_32x32x16_bf16 v[178:193], v[216:219], v[130:133], 0
	ds_read_b128 v[212:215], v230 offset:0
	ds_read_b128 v[216:219], v230 offset:8192
	s_waitcnt lgkmcnt(2)
	v_mfma_f32_32x32x16_bf16 v[162:177], v[220:223], v[134:137], v[162:177]
	v_mfma_f32_32x32x16_bf16 v[178:193], v[224:227], v[134:137], v[178:193]
	ds_read_b128 v[220:223], v231 offset:0
	ds_read_b128 v[224:227], v231 offset:8192
	s_waitcnt lgkmcnt(2)
	v_mfma_f32_32x32x16_bf16 v[162:177], v[212:215], v[138:141], v[162:177]
	v_mfma_f32_32x32x16_bf16 v[178:193], v[216:219], v[138:141], v[178:193]
	ds_read_b128 v[212:215], v232 offset:0
	ds_read_b128 v[216:219], v232 offset:8192
	s_waitcnt lgkmcnt(2)
	v_mfma_f32_32x32x16_bf16 v[162:177], v[220:223], v[142:145], v[162:177]
	v_mfma_f32_32x32x16_bf16 v[178:193], v[224:227], v[142:145], v[178:193]
	ds_read_b128 v[220:223], v233 offset:0
	ds_read_b128 v[224:227], v233 offset:8192
	s_waitcnt lgkmcnt(2)
	v_mfma_f32_32x32x16_bf16 v[162:177], v[212:215], v[146:149], v[162:177]
	v_mfma_f32_32x32x16_bf16 v[178:193], v[216:219], v[146:149], v[178:193]
	ds_read_b128 v[212:215], v234 offset:0
	ds_read_b128 v[216:219], v234 offset:8192
	s_waitcnt lgkmcnt(2)
	v_mfma_f32_32x32x16_bf16 v[162:177], v[220:223], v[150:153], v[162:177]
	v_mfma_f32_32x32x16_bf16 v[178:193], v[224:227], v[150:153], v[178:193]
	ds_read_b128 v[220:223], v235 offset:0
	ds_read_b128 v[224:227], v235 offset:8192
	s_waitcnt lgkmcnt(2)
	v_mfma_f32_32x32x16_bf16 v[162:177], v[212:215], v[154:157], v[162:177]
	v_mfma_f32_32x32x16_bf16 v[178:193], v[216:219], v[154:157], v[178:193]
	s_waitcnt lgkmcnt(0)
	v_mfma_f32_32x32x16_bf16 v[162:177], v[220:223], v[158:161], v[162:177]
	v_mfma_f32_32x32x16_bf16 v[178:193], v[224:227], v[158:161], v[178:193]
	ds_read_b64_tr_b16 v[212:213], v236 offset:0
	ds_read_b64_tr_b16 v[214:215], v236 offset:4096
	ds_read_b64_tr_b16 v[216:217], v236 offset:8192
	ds_read_b64_tr_b16 v[218:219], v236 offset:12288
	ds_read_b64_tr_b16 v[220:221], v236 offset:16384
	ds_read_b64_tr_b16 v[222:223], v236 offset:20480
	ds_read_b64_tr_b16 v[224:225], v236 offset:24576
	ds_read_b64_tr_b16 v[226:227], v236 offset:28672
	s_nop 4
	v_max_f32_e32 v240, v162, v163
	v_max3_f32 v240, v240, v164, v165
	v_max3_f32 v240, v240, v166, v167
	v_max3_f32 v240, v240, v168, v169
	v_max3_f32 v240, v240, v170, v171
	v_max3_f32 v240, v240, v172, v173
	v_max3_f32 v240, v240, v174, v175
	v_max3_f32 v240, v240, v176, v177
	v_max3_f32 v240, v240, v178, v179
	v_max3_f32 v240, v240, v180, v181
	v_max3_f32 v240, v240, v182, v183
	v_max3_f32 v240, v240, v184, v185
	v_max3_f32 v240, v240, v186, v187
	v_max3_f32 v240, v240, v188, v189
	v_max3_f32 v240, v240, v190, v191
	v_max3_f32 v240, v240, v192, v193
	v_mov_b32_e32 v241, v240
	s_nop 1
	v_permlane32_swap_b32_e32 v240, v241
	v_max_f32_e32 v240, v240, v241
	v_sub_f32_e32 v241, v240, v238
	v_cmp_ge_f32_e32 vcc, 0x42b504f3, v241
	s_nop 3
	s_cmp_eq_u64 vcc, exec
	s_cbranch_scc1 .Lam_keep_a
	v_max_f32_e32 v240, v238, v240
	v_sub_f32_e32 v241, v238, v240
	v_mul_f32_e32 v241, 0x3e0293ee, v241
	v_exp_f32_e32 v242, v241
	v_mov_b32_e32 v238, v240
	v_and_b32_e32 v240, 31, v96
	v_lshl_add_u32 v240, v240, 2, s50
	v_mul_f32_e32 v239, v239, v242
	ds_write_b32 v240, v242
	v_lshrrev_b32_e32 v240, 5, v96
	v_lshl_add_u32 v240, v240, 4, s50
	s_waitcnt lgkmcnt(0)
	ds_read_b128 v[196:199], v240 offset:0
	ds_read_b128 v[200:203], v240 offset:32
	ds_read_b128 v[204:207], v240 offset:64
	ds_read_b128 v[208:211], v240 offset:96
	s_waitcnt lgkmcnt(0)
	v_pk_mul_f32 v[0:1], v[0:1], v[196:197]
	v_pk_mul_f32 v[2:3], v[2:3], v[198:199]
	v_pk_mul_f32 v[4:5], v[4:5], v[200:201]
	v_pk_mul_f32 v[6:7], v[6:7], v[202:203]
	v_pk_mul_f32 v[8:9], v[8:9], v[204:205]
	v_pk_mul_f32 v[10:11], v[10:11], v[206:207]
	v_pk_mul_f32 v[12:13], v[12:13], v[208:209]
	v_pk_mul_f32 v[14:15], v[14:15], v[210:211]
	v_pk_mul_f32 v[16:17], v[16:17], v[196:197]
	v_pk_mul_f32 v[18:19], v[18:19], v[198:199]
	v_pk_mul_f32 v[20:21], v[20:21], v[200:201]
	v_pk_mul_f32 v[22:23], v[22:23], v[202:203]
	v_pk_mul_f32 v[24:25], v[24:25], v[204:205]
	v_pk_mul_f32 v[26:27], v[26:27], v[206:207]
	v_pk_mul_f32 v[28:29], v[28:29], v[208:209]
	v_pk_mul_f32 v[30:31], v[30:31], v[210:211]
	v_pk_mul_f32 v[32:33], v[32:33], v[196:197]
	v_pk_mul_f32 v[34:35], v[34:35], v[198:199]
	v_pk_mul_f32 v[36:37], v[36:37], v[200:201]
	v_pk_mul_f32 v[38:39], v[38:39], v[202:203]
	v_pk_mul_f32 v[40:41], v[40:41], v[204:205]
	v_pk_mul_f32 v[42:43], v[42:43], v[206:207]
	v_pk_mul_f32 v[44:45], v[44:45], v[208:209]
	v_pk_mul_f32 v[46:47], v[46:47], v[210:211]
	v_pk_mul_f32 v[48:49], v[48:49], v[196:197]
	v_pk_mul_f32 v[50:51], v[50:51], v[198:199]
	v_pk_mul_f32 v[52:53], v[52:53], v[200:201]
	v_pk_mul_f32 v[54:55], v[54:55], v[202:203]
	v_pk_mul_f32 v[56:57], v[56:57], v[204:205]
	v_pk_mul_f32 v[58:59], v[58:59], v[206:207]
	v_pk_mul_f32 v[60:61], v[60:61], v[208:209]
	v_pk_mul_f32 v[62:63], v[62:63], v[210:211]
	v_pk_mul_f32 v[64:65], v[64:65], v[196:197]
	v_pk_mul_f32 v[66:67], v[66:67], v[198:199]
	v_pk_mul_f32 v[68:69], v[68:69], v[200:201]
	v_pk_mul_f32 v[70:71], v[70:71], v[202:203]
	v_pk_mul_f32 v[72:73], v[72:73], v[204:205]
	v_pk_mul_f32 v[74:75], v[74:75], v[206:207]
	v_pk_mul_f32 v[76:77], v[76:77], v[208:209]
	v_pk_mul_f32 v[78:79], v[78:79], v[210:211]
	v_pk_mul_f32 v[80:81], v[80:81], v[196:197]
	v_pk_mul_f32 v[82:83], v[82:83], v[198:199]
	v_pk_mul_f32 v[84:85], v[84:85], v[200:201]
	v_pk_mul_f32 v[86:87], v[86:87], v[202:203]
	v_pk_mul_f32 v[88:89], v[88:89], v[204:205]
	v_pk_mul_f32 v[90:91], v[90:91], v[206:207]
	v_pk_mul_f32 v[92:93], v[92:93], v[208:209]
	v_pk_mul_f32 v[94:95], v[94:95], v[210:211]
	v_pk_mul_f32 v[98:99], v[98:99], v[196:197]
	v_pk_mul_f32 v[100:101], v[100:101], v[198:199]
	v_pk_mul_f32 v[102:103], v[102:103], v[200:201]
	v_pk_mul_f32 v[104:105], v[104:105], v[202:203]
	v_pk_mul_f32 v[106:107], v[106:107], v[204:205]
	v_pk_mul_f32 v[108:109], v[108:109], v[206:207]
	v_pk_mul_f32 v[110:111], v[110:111], v[208:209]
	v_pk_mul_f32 v[112:113], v[112:113], v[210:211]
	v_pk_mul_f32 v[114:115], v[114:115], v[196:197]
	v_pk_mul_f32 v[116:117], v[116:117], v[198:199]
	v_pk_mul_f32 v[118:119], v[118:119], v[200:201]
	v_pk_mul_f32 v[120:121], v[120:121], v[202:203]
	v_pk_mul_f32 v[122:123], v[122:123], v[204:205]
	v_pk_mul_f32 v[124:125], v[124:125], v[206:207]
	v_pk_mul_f32 v[126:127], v[126:127], v[208:209]
	v_pk_mul_f32 v[128:129], v[128:129], v[210:211]
.Lam_keep_a:
	v_mul_f32_e32 v243, 0xbe0293ee, v238
	v_fmamk_f32 v162, v162, 0x3e0293ee, v243
	v_fmamk_f32 v163, v163, 0x3e0293ee, v243
	v_fmamk_f32 v164, v164, 0x3e0293ee, v243
	v_fmamk_f32 v165, v165, 0x3e0293ee, v243
	v_fmamk_f32 v166, v166, 0x3e0293ee, v243
	v_fmamk_f32 v167, v167, 0x3e0293ee, v243
	v_fmamk_f32 v168, v168, 0x3e0293ee, v243
	v_fmamk_f32 v169, v169, 0x3e0293ee, v243
	v_fmamk_f32 v170, v170, 0x3e0293ee, v243
	v_fmamk_f32 v171, v171, 0x3e0293ee, v243
	v_fmamk_f32 v172, v172, 0x3e0293ee, v243
	v_fmamk_f32 v173, v173, 0x3e0293ee, v243
	v_fmamk_f32 v174, v174, 0x3e0293ee, v243
	v_fmamk_f32 v175, v175, 0x3e0293ee, v243
	v_fmamk_f32 v176, v176, 0x3e0293ee, v243
	v_fmamk_f32 v177, v177, 0x3e0293ee, v243
	v_fmamk_f32 v178, v178, 0x3e0293ee, v243
	v_fmamk_f32 v179, v179, 0x3e0293ee, v243
	v_fmamk_f32 v180, v180, 0x3e0293ee, v243
	v_fmamk_f32 v181, v181, 0x3e0293ee, v243
	v_fmamk_f32 v182, v182, 0x3e0293ee, v243
	v_fmamk_f32 v183, v183, 0x3e0293ee, v243
	v_fmamk_f32 v184, v184, 0x3e0293ee, v243
	v_fmamk_f32 v185, v185, 0x3e0293ee, v243
	v_fmamk_f32 v186, v186, 0x3e0293ee, v243
	v_fmamk_f32 v187, v187, 0x3e0293ee, v243
	v_fmamk_f32 v188, v188, 0x3e0293ee, v243
	v_fmamk_f32 v189, v189, 0x3e0293ee, v243
	v_fmamk_f32 v190, v190, 0x3e0293ee, v243
	v_fmamk_f32 v191, v191, 0x3e0293ee, v243
	v_fmamk_f32 v192, v192, 0x3e0293ee, v243
	v_fmamk_f32 v193, v193, 0x3e0293ee, v243
	v_exp_f32_e32 v162, v162
	v_exp_f32_e32 v163, v163
	v_exp_f32_e32 v164, v164
	v_exp_f32_e32 v165, v165
	v_exp_f32_e32 v166, v166
	v_exp_f32_e32 v167, v167
	v_exp_f32_e32 v168, v168
	v_exp_f32_e32 v169, v169
	v_exp_f32_e32 v170, v170
	v_exp_f32_e32 v171, v171
	v_exp_f32_e32 v172, v172
	v_exp_f32_e32 v173, v173
	v_exp_f32_e32 v174, v174
	v_exp_f32_e32 v175, v175
	v_exp_f32_e32 v176, v176
	v_exp_f32_e32 v177, v177
	v_exp_f32_e32 v178, v178
	v_exp_f32_e32 v179, v179
	v_exp_f32_e32 v180, v180
	v_exp_f32_e32 v181, v181
	v_exp_f32_e32 v182, v182
	v_exp_f32_e32 v183, v183
	v_exp_f32_e32 v184, v184
	v_exp_f32_e32 v185, v185
	v_exp_f32_e32 v186, v186
	v_exp_f32_e32 v187, v187
	v_exp_f32_e32 v188, v188
	v_exp_f32_e32 v189, v189
	v_exp_f32_e32 v190, v190
	v_exp_f32_e32 v191, v191
	v_exp_f32_e32 v192, v192
	v_exp_f32_e32 v193, v193
	v_add_f32_e32 v240, v162, v163
	v_add_f32_e32 v240, v240, v164
	v_add_f32_e32 v240, v240, v165
	v_add_f32_e32 v240, v240, v166
	v_add_f32_e32 v240, v240, v167
	v_add_f32_e32 v240, v240, v168
	v_add_f32_e32 v240, v240, v169
	v_add_f32_e32 v240, v240, v170
	v_add_f32_e32 v240, v240, v171
	v_add_f32_e32 v240, v240, v172
	v_add_f32_e32 v240, v240, v173
	v_add_f32_e32 v240, v240, v174
	v_add_f32_e32 v240, v240, v175
	v_add_f32_e32 v240, v240, v176
	v_add_f32_e32 v240, v240, v177
	v_add_f32_e32 v240, v240, v178
	v_add_f32_e32 v240, v240, v179
	v_add_f32_e32 v240, v240, v180
	v_add_f32_e32 v240, v240, v181
	v_add_f32_e32 v240, v240, v182
	v_add_f32_e32 v240, v240, v183
	v_add_f32_e32 v240, v240, v184
	v_add_f32_e32 v240, v240, v185
	v_add_f32_e32 v240, v240, v186
	v_add_f32_e32 v240, v240, v187
	v_add_f32_e32 v240, v240, v188
	v_add_f32_e32 v240, v240, v189
	v_add_f32_e32 v240, v240, v190
	v_add_f32_e32 v240, v240, v191
	v_add_f32_e32 v240, v240, v192
	v_add_f32_e32 v240, v240, v193
	v_mov_b32_e32 v241, v240
	v_cvt_pk_bf16_f32 v196, v162, v163
	v_cvt_pk_bf16_f32 v197, v164, v165
	v_cvt_pk_bf16_f32 v198, v166, v167
	v_cvt_pk_bf16_f32 v199, v168, v169
	v_cvt_pk_bf16_f32 v200, v170, v171
	v_cvt_pk_bf16_f32 v201, v172, v173
	v_cvt_pk_bf16_f32 v202, v174, v175
	v_cvt_pk_bf16_f32 v203, v176, v177
	v_cvt_pk_bf16_f32 v204, v178, v179
	v_cvt_pk_bf16_f32 v205, v180, v181
	v_cvt_pk_bf16_f32 v206, v182, v183
	v_cvt_pk_bf16_f32 v207, v184, v185
	v_cvt_pk_bf16_f32 v208, v186, v187
	v_cvt_pk_bf16_f32 v209, v188, v189
	v_cvt_pk_bf16_f32 v210, v190, v191
	v_cvt_pk_bf16_f32 v211, v192, v193
	s_nop 1
	v_permlane32_swap_b32_e32 v240, v241
	v_permlane32_swap_b32_e32 v196, v198
	v_permlane32_swap_b32_e32 v197, v199
	v_permlane32_swap_b32_e32 v200, v202
	v_permlane32_swap_b32_e32 v201, v203
	v_permlane32_swap_b32_e32 v204, v206
	v_permlane32_swap_b32_e32 v205, v207
	v_permlane32_swap_b32_e32 v208, v210
	v_permlane32_swap_b32_e32 v209, v211
	v_add_f32_e32 v240, v240, v241
	v_add_f32_e32 v239, v239, v240
	ds_read_b64_tr_b16 v[178:179], v236 offset:512
	ds_read_b64_tr_b16 v[180:181], v236 offset:4608
	ds_read_b64_tr_b16 v[182:183], v236 offset:8704
	ds_read_b64_tr_b16 v[184:185], v236 offset:12800
	ds_read_b64_tr_b16 v[186:187], v236 offset:16896
	ds_read_b64_tr_b16 v[188:189], v236 offset:20992
	ds_read_b64_tr_b16 v[190:191], v236 offset:25088
	ds_read_b64_tr_b16 v[192:193], v236 offset:29184
	s_waitcnt lgkmcnt(8)
	v_mfma_f32_32x32x16_bf16 v[0:15], v[196:199], v[212:215], v[0:15]
	v_mfma_f32_32x32x16_bf16 v[0:15], v[200:203], v[216:219], v[0:15]
	v_mfma_f32_32x32x16_bf16 v[0:15], v[204:207], v[220:223], v[0:15]
	v_mfma_f32_32x32x16_bf16 v[0:15], v[208:211], v[224:227], v[0:15]
	ds_read_b64_tr_b16 v[162:163], v236 offset:1024
	ds_read_b64_tr_b16 v[164:165], v236 offset:5120
	ds_read_b64_tr_b16 v[166:167], v236 offset:9216
	ds_read_b64_tr_b16 v[168:169], v236 offset:13312
	ds_read_b64_tr_b16 v[170:171], v236 offset:17408
	ds_read_b64_tr_b16 v[172:173], v236 offset:21504
	ds_read_b64_tr_b16 v[174:175], v236 offset:25600
	ds_read_b64_tr_b16 v[176:177], v236 offset:29696
	s_waitcnt lgkmcnt(8)
	v_mfma_f32_32x32x16_bf16 v[16:31], v[196:199], v[178:181], v[16:31]
	v_mfma_f32_32x32x16_bf16 v[16:31], v[200:203], v[182:185], v[16:31]
	v_mfma_f32_32x32x16_bf16 v[16:31], v[204:207], v[186:189], v[16:31]
	v_mfma_f32_32x32x16_bf16 v[16:31], v[208:211], v[190:193], v[16:31]
	ds_read_b64_tr_b16 v[178:179], v236 offset:1536
	ds_read_b64_tr_b16 v[180:181], v236 offset:5632
	ds_read_b64_tr_b16 v[182:183], v236 offset:9728
	ds_read_b64_tr_b16 v[184:185], v236 offset:13824
	ds_read_b64_tr_b16 v[186:187], v236 offset:17920
	ds_read_b64_tr_b16 v[188:189], v236 offset:22016
	ds_read_b64_tr_b16 v[190:191], v236 offset:26112
	ds_read_b64_tr_b16 v[192:193], v236 offset:30208
	s_waitcnt lgkmcnt(8)
	v_mfma_f32_32x32x16_bf16 v[32:47], v[196:199], v[162:165], v[32:47]
	v_mfma_f32_32x32x16_bf16 v[32:47], v[200:203], v[166:169], v[32:47]
	v_mfma_f32_32x32x16_bf16 v[32:47], v[204:207], v[170:173], v[32:47]
	v_mfma_f32_32x32x16_bf16 v[32:47], v[208:211], v[174:177], v[32:47]
	ds_read_b64_tr_b16 v[162:163], v236 offset:2048
	ds_read_b64_tr_b16 v[164:165], v236 offset:6144
	ds_read_b64_tr_b16 v[166:167], v236 offset:10240
	ds_read_b64_tr_b16 v[168:169], v236 offset:14336
	ds_read_b64_tr_b16 v[170:171], v236 offset:18432
	ds_read_b64_tr_b16 v[172:173], v236 offset:22528
	ds_read_b64_tr_b16 v[174:175], v236 offset:26624
	ds_read_b64_tr_b16 v[176:177], v236 offset:30720
	s_waitcnt lgkmcnt(8)
	v_mfma_f32_32x32x16_bf16 v[48:63], v[196:199], v[178:181], v[48:63]
	v_mfma_f32_32x32x16_bf16 v[48:63], v[200:203], v[182:185], v[48:63]
	v_mfma_f32_32x32x16_bf16 v[48:63], v[204:207], v[186:189], v[48:63]
	v_mfma_f32_32x32x16_bf16 v[48:63], v[208:211], v[190:193], v[48:63]
	ds_read_b64_tr_b16 v[178:179], v236 offset:2560
	ds_read_b64_tr_b16 v[180:181], v236 offset:6656
	ds_read_b64_tr_b16 v[182:183], v236 offset:10752
	ds_read_b64_tr_b16 v[184:185], v236 offset:14848
	ds_read_b64_tr_b16 v[186:187], v236 offset:18944
	ds_read_b64_tr_b16 v[188:189], v236 offset:23040
	ds_read_b64_tr_b16 v[190:191], v236 offset:27136
	ds_read_b64_tr_b16 v[192:193], v236 offset:31232
	s_waitcnt lgkmcnt(8)
	v_mfma_f32_32x32x16_bf16 v[64:79], v[196:199], v[162:165], v[64:79]
	v_mfma_f32_32x32x16_bf16 v[64:79], v[200:203], v[166:169], v[64:79]
	v_mfma_f32_32x32x16_bf16 v[64:79], v[204:207], v[170:173], v[64:79]
	v_mfma_f32_32x32x16_bf16 v[64:79], v[208:211], v[174:177], v[64:79]
	ds_read_b64_tr_b16 v[162:163], v236 offset:3072
	ds_read_b64_tr_b16 v[164:165], v236 offset:7168
	ds_read_b64_tr_b16 v[166:167], v236 offset:11264
	ds_read_b64_tr_b16 v[168:169], v236 offset:15360
	ds_read_b64_tr_b16 v[170:171], v236 offset:19456
	ds_read_b64_tr_b16 v[172:173], v236 offset:23552
	ds_read_b64_tr_b16 v[174:175], v236 offset:27648
	ds_read_b64_tr_b16 v[176:177], v236 offset:31744
	s_waitcnt lgkmcnt(8)
	v_mfma_f32_32x32x16_bf16 v[80:95], v[196:199], v[178:181], v[80:95]
	v_mfma_f32_32x32x16_bf16 v[80:95], v[200:203], v[182:185], v[80:95]
	v_mfma_f32_32x32x16_bf16 v[80:95], v[204:207], v[186:189], v[80:95]
	v_mfma_f32_32x32x16_bf16 v[80:95], v[208:211], v[190:193], v[80:95]
	ds_read_b64_tr_b16 v[178:179], v236 offset:3584
	ds_read_b64_tr_b16 v[180:181], v236 offset:7680
	ds_read_b64_tr_b16 v[182:183], v236 offset:11776
	ds_read_b64_tr_b16 v[184:185], v236 offset:15872
	ds_read_b64_tr_b16 v[186:187], v236 offset:19968
	ds_read_b64_tr_b16 v[188:189], v236 offset:24064
	ds_read_b64_tr_b16 v[190:191], v236 offset:28160
	ds_read_b64_tr_b16 v[192:193], v236 offset:32256
	s_waitcnt lgkmcnt(8)
	v_mfma_f32_32x32x16_bf16 v[98:113], v[196:199], v[162:165], v[98:113]
	v_mfma_f32_32x32x16_bf16 v[98:113], v[200:203], v[166:169], v[98:113]
	v_mfma_f32_32x32x16_bf16 v[98:113], v[204:207], v[170:173], v[98:113]
	v_mfma_f32_32x32x16_bf16 v[98:113], v[208:211], v[174:177], v[98:113]
	s_waitcnt lgkmcnt(0)
	v_mfma_f32_32x32x16_bf16 v[114:129], v[196:199], v[178:181], v[114:129]
	v_mfma_f32_32x32x16_bf16 v[114:129], v[200:203], v[182:185], v[114:129]
	v_mfma_f32_32x32x16_bf16 v[114:129], v[204:207], v[186:189], v[114:129]
	v_mfma_f32_32x32x16_bf16 v[114:129], v[208:211], v[190:193], v[114:129]
	s_waitcnt vmcnt(0)
	s_barrier
	s_cmp_le_u32 s13, 2
	s_cbranch_scc1 .Lam_nodma_a
	s_add_i32 m0, s39, 0x0
	s_nop 0
	global_load_lds_dwordx4 v244, s[18:19]
	s_add_i32 m0, s39, 0x400
	s_nop 0
	global_load_lds_dwordx4 v245, s[18:19]
	s_add_i32 m0, s47, 0x0
	s_nop 0
	global_load_lds_dwordx4 v246, s[20:21]
	s_add_i32 m0, s47, 0x400
	s_nop 0
	global_load_lds_dwordx4 v247, s[20:21]
	s_add_i32 m0, s47, 0x800
	s_nop 0
	global_load_lds_dwordx4 v248, s[20:21]
	s_add_i32 m0, s47, 0xc00
	s_nop 0
	global_load_lds_dwordx4 v249, s[20:21]
	s_add_u32 s18, s18, 0x40000
	s_addc_u32 s19, s19, 0
	s_add_u32 s20, s20, 0x40000
	s_addc_u32 s21, s21, 0
.Lam_nodma_a:
	ds_read_b128 v[212:215], v228 offset:49152
	ds_read_b128 v[216:219], v228 offset:57344
	ds_read_b128 v[220:223], v229 offset:49152
	ds_read_b128 v[224:227], v229 offset:57344
	s_waitcnt lgkmcnt(2)
	v_mfma_f32_32x32x16_bf16 v[162:177], v[212:215], v[130:133], 0
	v_mfma_f32_32x32x16_bf16 v[178:193], v[216:219], v[130:133], 0
	ds_read_b128 v[212:215], v230 offset:49152
	ds_read_b128 v[216:219], v230 offset:57344
	s_waitcnt lgkmcnt(2)
	v_mfma_f32_32x32x16_bf16 v[162:177], v[220:223], v[134:137], v[162:177]
	v_mfma_f32_32x32x16_bf16 v[178:193], v[224:227], v[134:137], v[178:193]
	ds_read_b128 v[220:223], v231 offset:49152
	ds_read_b128 v[224:227], v231 offset:57344
	s_waitcnt lgkmcnt(2)
	v_mfma_f32_32x32x16_bf16 v[162:177], v[212:215], v[138:141], v[162:177]
	v_mfma_f32_32x32x16_bf16 v[178:193], v[216:219], v[138:141], v[178:193]
	ds_read_b128 v[212:215], v232 offset:49152
	ds_read_b128 v[216:219], v232 offset:57344
	s_waitcnt lgkmcnt(2)
	v_mfma_f32_32x32x16_bf16 v[162:177], v[220:223], v[142:145], v[162:177]
	v_mfma_f32_32x32x16_bf16 v[178:193], v[224:227], v[142:145], v[178:193]
	ds_read_b128 v[220:223], v233 offset:49152
	ds_read_b128 v[224:227], v233 offset:57344
	s_waitcnt lgkmcnt(2)
	v_mfma_f32_32x32x16_bf16 v[162:177], v[212:215], v[146:149], v[162:177]
	v_mfma_f32_32x32x16_bf16 v[178:193], v[216:219], v[146:149], v[178:193]
	ds_read_b128 v[212:215], v234 offset:49152
	ds_read_b128 v[216:219], v234 offset:57344
	s_waitcnt lgkmcnt(2)
	v_mfma_f32_32x32x16_bf16 v[162:177], v[220:223], v[150:153], v[162:177]
	v_mfma_f32_32x32x16_bf16 v[178:193], v[224:227], v[150:153], v[178:193]
	ds_read_b128 v[220:223], v235 offset:49152
	ds_read_b128 v[224:227], v235 offset:57344
	s_waitcnt lgkmcnt(2)
	v_mfma_f32_32x32x16_bf16 v[162:177], v[212:215], v[154:157], v[162:177]
	v_mfma_f32_32x32x16_bf16 v[178:193], v[216:219], v[154:157], v[178:193]
	s_waitcnt lgkmcnt(0)
	v_mfma_f32_32x32x16_bf16 v[162:177], v[220:223], v[158:161], v[162:177]
	v_mfma_f32_32x32x16_bf16 v[178:193], v[224:227], v[158:161], v[178:193]
	ds_read_b64_tr_b16 v[212:213], v237 offset:0
	ds_read_b64_tr_b16 v[214:215], v237 offset:4096
	ds_read_b64_tr_b16 v[216:217], v237 offset:8192
	ds_read_b64_tr_b16 v[218:219], v237 offset:12288
	ds_read_b64_tr_b16 v[220:221], v237 offset:16384
	ds_read_b64_tr_b16 v[222:223], v237 offset:20480
	ds_read_b64_tr_b16 v[224:225], v237 offset:24576
	ds_read_b64_tr_b16 v[226:227], v237 offset:28672
	s_nop 4
	v_max_f32_e32 v240, v162, v163
	v_max3_f32 v240, v240, v164, v165
	v_max3_f32 v240, v240, v166, v167
	v_max3_f32 v240, v240, v168, v169
	v_max3_f32 v240, v240, v170, v171
	v_max3_f32 v240, v240, v172, v173
	v_max3_f32 v240, v240, v174, v175
	v_max3_f32 v240, v240, v176, v177
	v_max3_f32 v240, v240, v178, v179
	v_max3_f32 v240, v240, v180, v181
	v_max3_f32 v240, v240, v182, v183
	v_max3_f32 v240, v240, v184, v185
	v_max3_f32 v240, v240, v186, v187
	v_max3_f32 v240, v240, v188, v189
	v_max3_f32 v240, v240, v190, v191
	v_max3_f32 v240, v240, v192, v193
	v_mov_b32_e32 v241, v240
	s_nop 1
	v_permlane32_swap_b32_e32 v240, v241
	v_max_f32_e32 v240, v240, v241
	v_sub_f32_e32 v241, v240, v238
	v_cmp_ge_f32_e32 vcc, 0x42b504f3, v241
	s_nop 3
	s_cmp_eq_u64 vcc, exec
	s_cbranch_scc1 .Lam_keep_b
	v_max_f32_e32 v240, v238, v240
	v_sub_f32_e32 v241, v238, v240
	v_mul_f32_e32 v241, 0x3e0293ee, v241
	v_exp_f32_e32 v242, v241
	v_mov_b32_e32 v238, v240
	v_and_b32_e32 v240, 31, v96
	v_lshl_add_u32 v240, v240, 2, s50
	v_mul_f32_e32 v239, v239, v242
	ds_write_b32 v240, v242
	v_lshrrev_b32_e32 v240, 5, v96
	v_lshl_add_u32 v240, v240, 4, s50
	s_waitcnt lgkmcnt(0)
	ds_read_b128 v[196:199], v240 offset:0
	ds_read_b128 v[200:203], v240 offset:32
	ds_read_b128 v[204:207], v240 offset:64
	ds_read_b128 v[208:211], v240 offset:96
	s_waitcnt lgkmcnt(0)
	v_pk_mul_f32 v[0:1], v[0:1], v[196:197]
	v_pk_mul_f32 v[2:3], v[2:3], v[198:199]
	v_pk_mul_f32 v[4:5], v[4:5], v[200:201]
	v_pk_mul_f32 v[6:7], v[6:7], v[202:203]
	v_pk_mul_f32 v[8:9], v[8:9], v[204:205]
	v_pk_mul_f32 v[10:11], v[10:11], v[206:207]
	v_pk_mul_f32 v[12:13], v[12:13], v[208:209]
	v_pk_mul_f32 v[14:15], v[14:15], v[210:211]
	v_pk_mul_f32 v[16:17], v[16:17], v[196:197]
	v_pk_mul_f32 v[18:19], v[18:19], v[198:199]
	v_pk_mul_f32 v[20:21], v[20:21], v[200:201]
	v_pk_mul_f32 v[22:23], v[22:23], v[202:203]
	v_pk_mul_f32 v[24:25], v[24:25], v[204:205]
	v_pk_mul_f32 v[26:27], v[26:27], v[206:207]
	v_pk_mul_f32 v[28:29], v[28:29], v[208:209]
	v_pk_mul_f32 v[30:31], v[30:31], v[210:211]
	v_pk_mul_f32 v[32:33], v[32:33], v[196:197]
	v_pk_mul_f32 v[34:35], v[34:35], v[198:199]
	v_pk_mul_f32 v[36:37], v[36:37], v[200:201]
	v_pk_mul_f32 v[38:39], v[38:39], v[202:203]
	v_pk_mul_f32 v[40:41], v[40:41], v[204:205]
	v_pk_mul_f32 v[42:43], v[42:43], v[206:207]
	v_pk_mul_f32 v[44:45], v[44:45], v[208:209]
	v_pk_mul_f32 v[46:47], v[46:47], v[210:211]
	v_pk_mul_f32 v[48:49], v[48:49], v[196:197]
	v_pk_mul_f32 v[50:51], v[50:51], v[198:199]
	v_pk_mul_f32 v[52:53], v[52:53], v[200:201]
	v_pk_mul_f32 v[54:55], v[54:55], v[202:203]
	v_pk_mul_f32 v[56:57], v[56:57], v[204:205]
	v_pk_mul_f32 v[58:59], v[58:59], v[206:207]
	v_pk_mul_f32 v[60:61], v[60:61], v[208:209]
	v_pk_mul_f32 v[62:63], v[62:63], v[210:211]
	v_pk_mul_f32 v[64:65], v[64:65], v[196:197]
	v_pk_mul_f32 v[66:67], v[66:67], v[198:199]
	v_pk_mul_f32 v[68:69], v[68:69], v[200:201]
	v_pk_mul_f32 v[70:71], v[70:71], v[202:203]
	v_pk_mul_f32 v[72:73], v[72:73], v[204:205]
	v_pk_mul_f32 v[74:75], v[74:75], v[206:207]
	v_pk_mul_f32 v[76:77], v[76:77], v[208:209]
	v_pk_mul_f32 v[78:79], v[78:79], v[210:211]
	v_pk_mul_f32 v[80:81], v[80:81], v[196:197]
	v_pk_mul_f32 v[82:83], v[82:83], v[198:199]
	v_pk_mul_f32 v[84:85], v[84:85], v[200:201]
	v_pk_mul_f32 v[86:87], v[86:87], v[202:203]
	v_pk_mul_f32 v[88:89], v[88:89], v[204:205]
	v_pk_mul_f32 v[90:91], v[90:91], v[206:207]
	v_pk_mul_f32 v[92:93], v[92:93], v[208:209]
	v_pk_mul_f32 v[94:95], v[94:95], v[210:211]
	v_pk_mul_f32 v[98:99], v[98:99], v[196:197]
	v_pk_mul_f32 v[100:101], v[100:101], v[198:199]
	v_pk_mul_f32 v[102:103], v[102:103], v[200:201]
	v_pk_mul_f32 v[104:105], v[104:105], v[202:203]
	v_pk_mul_f32 v[106:107], v[106:107], v[204:205]
	v_pk_mul_f32 v[108:109], v[108:109], v[206:207]
	v_pk_mul_f32 v[110:111], v[110:111], v[208:209]
	v_pk_mul_f32 v[112:113], v[112:113], v[210:211]
	v_pk_mul_f32 v[114:115], v[114:115], v[196:197]
	v_pk_mul_f32 v[116:117], v[116:117], v[198:199]
	v_pk_mul_f32 v[118:119], v[118:119], v[200:201]
	v_pk_mul_f32 v[120:121], v[120:121], v[202:203]
	v_pk_mul_f32 v[122:123], v[122:123], v[204:205]
	v_pk_mul_f32 v[124:125], v[124:125], v[206:207]
	v_pk_mul_f32 v[126:127], v[126:127], v[208:209]
	v_pk_mul_f32 v[128:129], v[128:129], v[210:211]
.Lam_keep_b:
	v_mul_f32_e32 v243, 0xbe0293ee, v238
	v_fmamk_f32 v162, v162, 0x3e0293ee, v243
	v_fmamk_f32 v163, v163, 0x3e0293ee, v243
	v_fmamk_f32 v164, v164, 0x3e0293ee, v243
	v_fmamk_f32 v165, v165, 0x3e0293ee, v243
	v_fmamk_f32 v166, v166, 0x3e0293ee, v243
	v_fmamk_f32 v167, v167, 0x3e0293ee, v243
	v_fmamk_f32 v168, v168, 0x3e0293ee, v243
	v_fmamk_f32 v169, v169, 0x3e0293ee, v243
	v_fmamk_f32 v170, v170, 0x3e0293ee, v243
	v_fmamk_f32 v171, v171, 0x3e0293ee, v243
	v_fmamk_f32 v172, v172, 0x3e0293ee, v243
	v_fmamk_f32 v173, v173, 0x3e0293ee, v243
	v_fmamk_f32 v174, v174, 0x3e0293ee, v243
	v_fmamk_f32 v175, v175, 0x3e0293ee, v243
	v_fmamk_f32 v176, v176, 0x3e0293ee, v243
	v_fmamk_f32 v177, v177, 0x3e0293ee, v243
	v_fmamk_f32 v178, v178, 0x3e0293ee, v243
	v_fmamk_f32 v179, v179, 0x3e0293ee, v243
	v_fmamk_f32 v180, v180, 0x3e0293ee, v243
	v_fmamk_f32 v181, v181, 0x3e0293ee, v243
	v_fmamk_f32 v182, v182, 0x3e0293ee, v243
	v_fmamk_f32 v183, v183, 0x3e0293ee, v243
	v_fmamk_f32 v184, v184, 0x3e0293ee, v243
	v_fmamk_f32 v185, v185, 0x3e0293ee, v243
	v_fmamk_f32 v186, v186, 0x3e0293ee, v243
	v_fmamk_f32 v187, v187, 0x3e0293ee, v243
	v_fmamk_f32 v188, v188, 0x3e0293ee, v243
	v_fmamk_f32 v189, v189, 0x3e0293ee, v243
	v_fmamk_f32 v190, v190, 0x3e0293ee, v243
	v_fmamk_f32 v191, v191, 0x3e0293ee, v243
	v_fmamk_f32 v192, v192, 0x3e0293ee, v243
	v_fmamk_f32 v193, v193, 0x3e0293ee, v243
	v_exp_f32_e32 v162, v162
	v_exp_f32_e32 v163, v163
	v_exp_f32_e32 v164, v164
	v_exp_f32_e32 v165, v165
	v_exp_f32_e32 v166, v166
	v_exp_f32_e32 v167, v167
	v_exp_f32_e32 v168, v168
	v_exp_f32_e32 v169, v169
	v_exp_f32_e32 v170, v170
	v_exp_f32_e32 v171, v171
	v_exp_f32_e32 v172, v172
	v_exp_f32_e32 v173, v173
	v_exp_f32_e32 v174, v174
	v_exp_f32_e32 v175, v175
	v_exp_f32_e32 v176, v176
	v_exp_f32_e32 v177, v177
	v_exp_f32_e32 v178, v178
	v_exp_f32_e32 v179, v179
	v_exp_f32_e32 v180, v180
	v_exp_f32_e32 v181, v181
	v_exp_f32_e32 v182, v182
	v_exp_f32_e32 v183, v183
	v_exp_f32_e32 v184, v184
	v_exp_f32_e32 v185, v185
	v_exp_f32_e32 v186, v186
	v_exp_f32_e32 v187, v187
	v_exp_f32_e32 v188, v188
	v_exp_f32_e32 v189, v189
	v_exp_f32_e32 v190, v190
	v_exp_f32_e32 v191, v191
	v_exp_f32_e32 v192, v192
	v_exp_f32_e32 v193, v193
	v_add_f32_e32 v240, v162, v163
	v_add_f32_e32 v240, v240, v164
	v_add_f32_e32 v240, v240, v165
	v_add_f32_e32 v240, v240, v166
	v_add_f32_e32 v240, v240, v167
	v_add_f32_e32 v240, v240, v168
	v_add_f32_e32 v240, v240, v169
	v_add_f32_e32 v240, v240, v170
	v_add_f32_e32 v240, v240, v171
	v_add_f32_e32 v240, v240, v172
	v_add_f32_e32 v240, v240, v173
	v_add_f32_e32 v240, v240, v174
	v_add_f32_e32 v240, v240, v175
	v_add_f32_e32 v240, v240, v176
	v_add_f32_e32 v240, v240, v177
	v_add_f32_e32 v240, v240, v178
	v_add_f32_e32 v240, v240, v179
	v_add_f32_e32 v240, v240, v180
	v_add_f32_e32 v240, v240, v181
	v_add_f32_e32 v240, v240, v182
	v_add_f32_e32 v240, v240, v183
	v_add_f32_e32 v240, v240, v184
	v_add_f32_e32 v240, v240, v185
	v_add_f32_e32 v240, v240, v186
	v_add_f32_e32 v240, v240, v187
	v_add_f32_e32 v240, v240, v188
	v_add_f32_e32 v240, v240, v189
	v_add_f32_e32 v240, v240, v190
	v_add_f32_e32 v240, v240, v191
	v_add_f32_e32 v240, v240, v192
	v_add_f32_e32 v240, v240, v193
	v_mov_b32_e32 v241, v240
	v_cvt_pk_bf16_f32 v196, v162, v163
	v_cvt_pk_bf16_f32 v197, v164, v165
	v_cvt_pk_bf16_f32 v198, v166, v167
	v_cvt_pk_bf16_f32 v199, v168, v169
	v_cvt_pk_bf16_f32 v200, v170, v171
	v_cvt_pk_bf16_f32 v201, v172, v173
	v_cvt_pk_bf16_f32 v202, v174, v175
	v_cvt_pk_bf16_f32 v203, v176, v177
	v_cvt_pk_bf16_f32 v204, v178, v179
	v_cvt_pk_bf16_f32 v205, v180, v181
	v_cvt_pk_bf16_f32 v206, v182, v183
	v_cvt_pk_bf16_f32 v207, v184, v185
	v_cvt_pk_bf16_f32 v208, v186, v187
	v_cvt_pk_bf16_f32 v209, v188, v189
	v_cvt_pk_bf16_f32 v210, v190, v191
	v_cvt_pk_bf16_f32 v211, v192, v193
	s_nop 1
	v_permlane32_swap_b32_e32 v240, v241
	v_permlane32_swap_b32_e32 v196, v198
	v_permlane32_swap_b32_e32 v197, v199
	v_permlane32_swap_b32_e32 v200, v202
	v_permlane32_swap_b32_e32 v201, v203
	v_permlane32_swap_b32_e32 v204, v206
	v_permlane32_swap_b32_e32 v205, v207
	v_permlane32_swap_b32_e32 v208, v210
	v_permlane32_swap_b32_e32 v209, v211
	v_add_f32_e32 v240, v240, v241
	v_add_f32_e32 v239, v239, v240
	ds_read_b64_tr_b16 v[178:179], v237 offset:512
	ds_read_b64_tr_b16 v[180:181], v237 offset:4608
	ds_read_b64_tr_b16 v[182:183], v237 offset:8704
	ds_read_b64_tr_b16 v[184:185], v237 offset:12800
	ds_read_b64_tr_b16 v[186:187], v237 offset:16896
	ds_read_b64_tr_b16 v[188:189], v237 offset:20992
	ds_read_b64_tr_b16 v[190:191], v237 offset:25088
	ds_read_b64_tr_b16 v[192:193], v237 offset:29184
	s_waitcnt lgkmcnt(8)
	v_mfma_f32_32x32x16_bf16 v[0:15], v[196:199], v[212:215], v[0:15]
	v_mfma_f32_32x32x16_bf16 v[0:15], v[200:203], v[216:219], v[0:15]
	v_mfma_f32_32x32x16_bf16 v[0:15], v[204:207], v[220:223], v[0:15]
	v_mfma_f32_32x32x16_bf16 v[0:15], v[208:211], v[224:227], v[0:15]
	ds_read_b64_tr_b16 v[162:163], v237 offset:1024
	ds_read_b64_tr_b16 v[164:165], v237 offset:5120
	ds_read_b64_tr_b16 v[166:167], v237 offset:9216
	ds_read_b64_tr_b16 v[168:169], v237 offset:13312
	ds_read_b64_tr_b16 v[170:171], v237 offset:17408
	ds_read_b64_tr_b16 v[172:173], v237 offset:21504
	ds_read_b64_tr_b16 v[174:175], v237 offset:25600
	ds_read_b64_tr_b16 v[176:177], v237 offset:29696
	s_waitcnt lgkmcnt(8)
	v_mfma_f32_32x32x16_bf16 v[16:31], v[196:199], v[178:181], v[16:31]
	v_mfma_f32_32x32x16_bf16 v[16:31], v[200:203], v[182:185], v[16:31]
	v_mfma_f32_32x32x16_bf16 v[16:31], v[204:207], v[186:189], v[16:31]
	v_mfma_f32_32x32x16_bf16 v[16:31], v[208:211], v[190:193], v[16:31]
	ds_read_b64_tr_b16 v[178:179], v237 offset:1536
	ds_read_b64_tr_b16 v[180:181], v237 offset:5632
	ds_read_b64_tr_b16 v[182:183], v237 offset:9728
	ds_read_b64_tr_b16 v[184:185], v237 offset:13824
	ds_read_b64_tr_b16 v[186:187], v237 offset:17920
	ds_read_b64_tr_b16 v[188:189], v237 offset:22016
	ds_read_b64_tr_b16 v[190:191], v237 offset:26112
	ds_read_b64_tr_b16 v[192:193], v237 offset:30208
	s_waitcnt lgkmcnt(8)
	v_mfma_f32_32x32x16_bf16 v[32:47], v[196:199], v[162:165], v[32:47]
	v_mfma_f32_32x32x16_bf16 v[32:47], v[200:203], v[166:169], v[32:47]
	v_mfma_f32_32x32x16_bf16 v[32:47], v[204:207], v[170:173], v[32:47]
	v_mfma_f32_32x32x16_bf16 v[32:47], v[208:211], v[174:177], v[32:47]
	ds_read_b64_tr_b16 v[162:163], v237 offset:2048
	ds_read_b64_tr_b16 v[164:165], v237 offset:6144
	ds_read_b64_tr_b16 v[166:167], v237 offset:10240
	ds_read_b64_tr_b16 v[168:169], v237 offset:14336
	ds_read_b64_tr_b16 v[170:171], v237 offset:18432
	ds_read_b64_tr_b16 v[172:173], v237 offset:22528
	ds_read_b64_tr_b16 v[174:175], v237 offset:26624
	ds_read_b64_tr_b16 v[176:177], v237 offset:30720
	s_waitcnt lgkmcnt(8)
	v_mfma_f32_32x32x16_bf16 v[48:63], v[196:199], v[178:181], v[48:63]
	v_mfma_f32_32x32x16_bf16 v[48:63], v[200:203], v[182:185], v[48:63]
	v_mfma_f32_32x32x16_bf16 v[48:63], v[204:207], v[186:189], v[48:63]
	v_mfma_f32_32x32x16_bf16 v[48:63], v[208:211], v[190:193], v[48:63]
	ds_read_b64_tr_b16 v[178:179], v237 offset:2560
	ds_read_b64_tr_b16 v[180:181], v237 offset:6656
	ds_read_b64_tr_b16 v[182:183], v237 offset:10752
	ds_read_b64_tr_b16 v[184:185], v237 offset:14848
	ds_read_b64_tr_b16 v[186:187], v237 offset:18944
	ds_read_b64_tr_b16 v[188:189], v237 offset:23040
	ds_read_b64_tr_b16 v[190:191], v237 offset:27136
	ds_read_b64_tr_b16 v[192:193], v237 offset:31232
	s_waitcnt lgkmcnt(8)
	v_mfma_f32_32x32x16_bf16 v[64:79], v[196:199], v[162:165], v[64:79]
	v_mfma_f32_32x32x16_bf16 v[64:79], v[200:203], v[166:169], v[64:79]
	v_mfma_f32_32x32x16_bf16 v[64:79], v[204:207], v[170:173], v[64:79]
	v_mfma_f32_32x32x16_bf16 v[64:79], v[208:211], v[174:177], v[64:79]
	ds_read_b64_tr_b16 v[162:163], v237 offset:3072
	ds_read_b64_tr_b16 v[164:165], v237 offset:7168
	ds_read_b64_tr_b16 v[166:167], v237 offset:11264
	ds_read_b64_tr_b16 v[168:169], v237 offset:15360
	ds_read_b64_tr_b16 v[170:171], v237 offset:19456
	ds_read_b64_tr_b16 v[172:173], v237 offset:23552
	ds_read_b64_tr_b16 v[174:175], v237 offset:27648
	ds_read_b64_tr_b16 v[176:177], v237 offset:31744
	s_waitcnt lgkmcnt(8)
	v_mfma_f32_32x32x16_bf16 v[80:95], v[196:199], v[178:181], v[80:95]
	v_mfma_f32_32x32x16_bf16 v[80:95], v[200:203], v[182:185], v[80:95]
	v_mfma_f32_32x32x16_bf16 v[80:95], v[204:207], v[186:189], v[80:95]
	v_mfma_f32_32x32x16_bf16 v[80:95], v[208:211], v[190:193], v[80:95]
	ds_read_b64_tr_b16 v[178:179], v237 offset:3584
	ds_read_b64_tr_b16 v[180:181], v237 offset:7680
	ds_read_b64_tr_b16 v[182:183], v237 offset:11776
	ds_read_b64_tr_b16 v[184:185], v237 offset:15872
	ds_read_b64_tr_b16 v[186:187], v237 offset:19968
	ds_read_b64_tr_b16 v[188:189], v237 offset:24064
	ds_read_b64_tr_b16 v[190:191], v237 offset:28160
	ds_read_b64_tr_b16 v[192:193], v237 offset:32256
	s_waitcnt lgkmcnt(8)
	v_mfma_f32_32x32x16_bf16 v[98:113], v[196:199], v[162:165], v[98:113]
	v_mfma_f32_32x32x16_bf16 v[98:113], v[200:203], v[166:169], v[98:113]
	v_mfma_f32_32x32x16_bf16 v[98:113], v[204:207], v[170:173], v[98:113]
	v_mfma_f32_32x32x16_bf16 v[98:113], v[208:211], v[174:177], v[98:113]
	s_waitcnt lgkmcnt(0)
	v_mfma_f32_32x32x16_bf16 v[114:129], v[196:199], v[178:181], v[114:129]
	v_mfma_f32_32x32x16_bf16 v[114:129], v[200:203], v[182:185], v[114:129]
	v_mfma_f32_32x32x16_bf16 v[114:129], v[204:207], v[186:189], v[114:129]
	v_mfma_f32_32x32x16_bf16 v[114:129], v[208:211], v[190:193], v[114:129]
	s_waitcnt vmcnt(0)
	s_barrier
	s_cmp_le_u32 s13, 3
	s_cbranch_scc1 .Lam_nodma_b
	s_add_i32 m0, s39, 0xc000
	s_nop 0
	global_load_lds_dwordx4 v244, s[18:19]
	s_add_i32 m0, s39, 0xc400
	s_nop 0
	global_load_lds_dwordx4 v245, s[18:19]
	s_add_i32 m0, s47, 0xc000
	s_nop 0
	global_load_lds_dwordx4 v246, s[20:21]
	s_add_i32 m0, s47, 0xc400
	s_nop 0
	global_load_lds_dwordx4 v247, s[20:21]
	s_add_i32 m0, s47, 0xc800
	s_nop 0
	global_load_lds_dwordx4 v248, s[20:21]
	s_add_i32 m0, s47, 0xcc00
	s_nop 0
	global_load_lds_dwordx4 v249, s[20:21]
	s_add_u32 s18, s18, 0x40000
	s_addc_u32 s19, s19, 0
	s_add_u32 s20, s20, 0x40000
	s_addc_u32 s21, s21, 0
.Lam_nodma_b:
	s_sub_i32 s13, s13, 2
	s_cmp_gt_u32 s13, 0
	s_cbranch_scc1 .Lam_loop
	v_and_b32_e32 v240, 31, v96
	v_lshl_add_u32 v241, v240, 2, s50
	ds_write_b32 v241, v239 offset:128
	v_lshrrev_b32_e32 v241, 5, v96
	v_lshl_add_u32 v242, v241, 4, s50
	s_waitcnt lgkmcnt(0)
	ds_read_b128 v[212:215], v242 offset:128
	ds_read_b128 v[216:219], v242 offset:160
	ds_read_b128 v[220:223], v242 offset:192
	ds_read_b128 v[224:227], v242 offset:224
	s_lshl_b32 s37, s36, 5
	v_lshl_add_u32 v241, v241, 2, s37
	v_lshlrev_b32_e32 v241, 13, v241
	v_lshl_add_u32 v241, v240, 1, v241
	s_waitcnt lgkmcnt(0)
	v_rcp_f32_e32 v212, v212
	v_rcp_f32_e32 v213, v213
	v_rcp_f32_e32 v214, v214
	v_rcp_f32_e32 v215, v215
	v_rcp_f32_e32 v216, v216
	v_rcp_f32_e32 v217, v217
	v_rcp_f32_e32 v218, v218
	v_rcp_f32_e32 v219, v219
	v_rcp_f32_e32 v220, v220
	v_rcp_f32_e32 v221, v221
	v_rcp_f32_e32 v222, v222
	v_rcp_f32_e32 v223, v223
	v_rcp_f32_e32 v224, v224
	v_rcp_f32_e32 v225, v225
	v_rcp_f32_e32 v226, v226
	v_rcp_f32_e32 v227, v227
	s_nop 0
	v_mov_b32_e32 v240, v241
	v_mul_f32_e32 v162, v0, v212
	v_mul_f32_e32 v163, v16, v212
	v_cvt_pk_bf16_f32 v162, v162, v163
	global_store_short v240, v162, s[22:23]
	global_store_short_d16_hi v240, v162, s[22:23] offset:64
	v_mul_f32_e32 v164, v32, v212
	v_mul_f32_e32 v165, v48, v212
	v_cvt_pk_bf16_f32 v164, v164, v165
	global_store_short v240, v164, s[22:23] offset:128
	global_store_short_d16_hi v240, v164, s[22:23] offset:192
	v_mul_f32_e32 v166, v64, v212
	v_mul_f32_e32 v167, v80, v212
	v_cvt_pk_bf16_f32 v166, v166, v167
	global_store_short v240, v166, s[22:23] offset:256
	global_store_short_d16_hi v240, v166, s[22:23] offset:320
	v_mul_f32_e32 v168, v98, v212
	v_mul_f32_e32 v169, v114, v212
	v_cvt_pk_bf16_f32 v168, v168, v169
	global_store_short v240, v168, s[22:23] offset:384
	global_store_short_d16_hi v240, v168, s[22:23] offset:448
	v_add_u32_e32 v240, 0x2000, v241
	v_mul_f32_e32 v170, v1, v213
	v_mul_f32_e32 v171, v17, v213
	v_cvt_pk_bf16_f32 v170, v170, v171
	global_store_short v240, v170, s[22:23]
	global_store_short_d16_hi v240, v170, s[22:23] offset:64
	v_mul_f32_e32 v172, v33, v213
	v_mul_f32_e32 v173, v49, v213
	v_cvt_pk_bf16_f32 v172, v172, v173
	global_store_short v240, v172, s[22:23] offset:128
	global_store_short_d16_hi v240, v172, s[22:23] offset:192
	v_mul_f32_e32 v174, v65, v213
	v_mul_f32_e32 v175, v81, v213
	v_cvt_pk_bf16_f32 v174, v174, v175
	global_store_short v240, v174, s[22:23] offset:256
	global_store_short_d16_hi v240, v174, s[22:23] offset:320
	v_mul_f32_e32 v176, v99, v213
	v_mul_f32_e32 v177, v115, v213
	v_cvt_pk_bf16_f32 v176, v176, v177
	global_store_short v240, v176, s[22:23] offset:384
	global_store_short_d16_hi v240, v176, s[22:23] offset:448
	v_add_u32_e32 v240, 0x4000, v241
	v_mul_f32_e32 v178, v2, v214
	v_mul_f32_e32 v179, v18, v214
	v_cvt_pk_bf16_f32 v178, v178, v179
	global_store_short v240, v178, s[22:23]
	global_store_short_d16_hi v240, v178, s[22:23] offset:64
	v_mul_f32_e32 v180, v34, v214
	v_mul_f32_e32 v181, v50, v214
	v_cvt_pk_bf16_f32 v180, v180, v181
	global_store_short v240, v180, s[22:23] offset:128
	global_store_short_d16_hi v240, v180, s[22:23] offset:192
	v_mul_f32_e32 v182, v66, v214
	v_mul_f32_e32 v183, v82, v214
	v_cvt_pk_bf16_f32 v182, v182, v183
	global_store_short v240, v182, s[22:23] offset:256
	global_store_short_d16_hi v240, v182, s[22:23] offset:320
	v_mul_f32_e32 v184, v100, v214
	v_mul_f32_e32 v185, v116, v214
	v_cvt_pk_bf16_f32 v184, v184, v185
	global_store_short v240, v184, s[22:23] offset:384
	global_store_short_d16_hi v240, v184, s[22:23] offset:448
	v_add_u32_e32 v240, 0x6000, v241
	v_mul_f32_e32 v186, v3, v215
	v_mul_f32_e32 v187, v19, v215
	v_cvt_pk_bf16_f32 v186, v186, v187
	global_store_short v240, v186, s[22:23]
	global_store_short_d16_hi v240, v186, s[22:23] offset:64
	v_mul_f32_e32 v188, v35, v215
	v_mul_f32_e32 v189, v51, v215
	v_cvt_pk_bf16_f32 v188, v188, v189
	global_store_short v240, v188, s[22:23] offset:128
	global_store_short_d16_hi v240, v188, s[22:23] offset:192
	v_mul_f32_e32 v190, v67, v215
	v_mul_f32_e32 v191, v83, v215
	v_cvt_pk_bf16_f32 v190, v190, v191
	global_store_short v240, v190, s[22:23] offset:256
	global_store_short_d16_hi v240, v190, s[22:23] offset:320
	v_mul_f32_e32 v192, v101, v215
	v_mul_f32_e32 v193, v117, v215
	v_cvt_pk_bf16_f32 v192, v192, v193
	global_store_short v240, v192, s[22:23] offset:384
	global_store_short_d16_hi v240, v192, s[22:23] offset:448
	v_add_u32_e32 v240, 0x10000, v241
	v_mul_f32_e32 v162, v4, v216
	v_mul_f32_e32 v163, v20, v216
	v_cvt_pk_bf16_f32 v162, v162, v163
	global_store_short v240, v162, s[22:23]
	global_store_short_d16_hi v240, v162, s[22:23] offset:64
	v_mul_f32_e32 v164, v36, v216
	v_mul_f32_e32 v165, v52, v216
	v_cvt_pk_bf16_f32 v164, v164, v165
	global_store_short v240, v164, s[22:23] offset:128
	global_store_short_d16_hi v240, v164, s[22:23] offset:192
	v_mul_f32_e32 v166, v68, v216
	v_mul_f32_e32 v167, v84, v216
	v_cvt_pk_bf16_f32 v166, v166, v167
	global_store_short v240, v166, s[22:23] offset:256
	global_store_short_d16_hi v240, v166, s[22:23] offset:320
	v_mul_f32_e32 v168, v102, v216
	v_mul_f32_e32 v169, v118, v216
	v_cvt_pk_bf16_f32 v168, v168, v169
	global_store_short v240, v168, s[22:23] offset:384
	global_store_short_d16_hi v240, v168, s[22:23] offset:448
	v_add_u32_e32 v240, 0x12000, v241
	v_mul_f32_e32 v170, v5, v217
	v_mul_f32_e32 v171, v21, v217
	v_cvt_pk_bf16_f32 v170, v170, v171
	global_store_short v240, v170, s[22:23]
	global_store_short_d16_hi v240, v170, s[22:23] offset:64
	v_mul_f32_e32 v172, v37, v217
	v_mul_f32_e32 v173, v53, v217
	v_cvt_pk_bf16_f32 v172, v172, v173
	global_store_short v240, v172, s[22:23] offset:128
	global_store_short_d16_hi v240, v172, s[22:23] offset:192
	v_mul_f32_e32 v174, v69, v217
	v_mul_f32_e32 v175, v85, v217
	v_cvt_pk_bf16_f32 v174, v174, v175
	global_store_short v240, v174, s[22:23] offset:256
	global_store_short_d16_hi v240, v174, s[22:23] offset:320
	v_mul_f32_e32 v176, v103, v217
	v_mul_f32_e32 v177, v119, v217
	v_cvt_pk_bf16_f32 v176, v176, v177
	global_store_short v240, v176, s[22:23] offset:384
	global_store_short_d16_hi v240, v176, s[22:23] offset:448
	v_add_u32_e32 v240, 0x14000, v241
	v_mul_f32_e32 v178, v6, v218
	v_mul_f32_e32 v179, v22, v218
	v_cvt_pk_bf16_f32 v178, v178, v179
	global_store_short v240, v178, s[22:23]
	global_store_short_d16_hi v240, v178, s[22:23] offset:64
	v_mul_f32_e32 v180, v38, v218
	v_mul_f32_e32 v181, v54, v218
	v_cvt_pk_bf16_f32 v180, v180, v181
	global_store_short v240, v180, s[22:23] offset:128
	global_store_short_d16_hi v240, v180, s[22:23] offset:192
	v_mul_f32_e32 v182, v70, v218
	v_mul_f32_e32 v183, v86, v218
	v_cvt_pk_bf16_f32 v182, v182, v183
	global_store_short v240, v182, s[22:23] offset:256
	global_store_short_d16_hi v240, v182, s[22:23] offset:320
	v_mul_f32_e32 v184, v104, v218
	v_mul_f32_e32 v185, v120, v218
	v_cvt_pk_bf16_f32 v184, v184, v185
	global_store_short v240, v184, s[22:23] offset:384
	global_store_short_d16_hi v240, v184, s[22:23] offset:448
	v_add_u32_e32 v240, 0x16000, v241
	v_mul_f32_e32 v186, v7, v219
	v_mul_f32_e32 v187, v23, v219
	v_cvt_pk_bf16_f32 v186, v186, v187
	global_store_short v240, v186, s[22:23]
	global_store_short_d16_hi v240, v186, s[22:23] offset:64
	v_mul_f32_e32 v188, v39, v219
	v_mul_f32_e32 v189, v55, v219
	v_cvt_pk_bf16_f32 v188, v188, v189
	global_store_short v240, v188, s[22:23] offset:128
	global_store_short_d16_hi v240, v188, s[22:23] offset:192
	v_mul_f32_e32 v190, v71, v219
	v_mul_f32_e32 v191, v87, v219
	v_cvt_pk_bf16_f32 v190, v190, v191
	global_store_short v240, v190, s[22:23] offset:256
	global_store_short_d16_hi v240, v190, s[22:23] offset:320
	v_mul_f32_e32 v192, v105, v219
	v_mul_f32_e32 v193, v121, v219
	v_cvt_pk_bf16_f32 v192, v192, v193
	global_store_short v240, v192, s[22:23] offset:384
	global_store_short_d16_hi v240, v192, s[22:23] offset:448
	v_add_u32_e32 v240, 0x20000, v241
	v_mul_f32_e32 v162, v8, v220
	v_mul_f32_e32 v163, v24, v220
	v_cvt_pk_bf16_f32 v162, v162, v163
	global_store_short v240, v162, s[22:23]
	global_store_short_d16_hi v240, v162, s[22:23] offset:64
	v_mul_f32_e32 v164, v40, v220
	v_mul_f32_e32 v165, v56, v220
	v_cvt_pk_bf16_f32 v164, v164, v165
	global_store_short v240, v164, s[22:23] offset:128
	global_store_short_d16_hi v240, v164, s[22:23] offset:192
	v_mul_f32_e32 v166, v72, v220
	v_mul_f32_e32 v167, v88, v220
	v_cvt_pk_bf16_f32 v166, v166, v167
	global_store_short v240, v166, s[22:23] offset:256
	global_store_short_d16_hi v240, v166, s[22:23] offset:320
	v_mul_f32_e32 v168, v106, v220
	v_mul_f32_e32 v169, v122, v220
	v_cvt_pk_bf16_f32 v168, v168, v169
	global_store_short v240, v168, s[22:23] offset:384
	global_store_short_d16_hi v240, v168, s[22:23] offset:448
	v_add_u32_e32 v240, 0x22000, v241
	v_mul_f32_e32 v170, v9, v221
	v_mul_f32_e32 v171, v25, v221
	v_cvt_pk_bf16_f32 v170, v170, v171
	global_store_short v240, v170, s[22:23]
	global_store_short_d16_hi v240, v170, s[22:23] offset:64
	v_mul_f32_e32 v172, v41, v221
	v_mul_f32_e32 v173, v57, v221
	v_cvt_pk_bf16_f32 v172, v172, v173
	global_store_short v240, v172, s[22:23] offset:128
	global_store_short_d16_hi v240, v172, s[22:23] offset:192
	v_mul_f32_e32 v174, v73, v221
	v_mul_f32_e32 v175, v89, v221
	v_cvt_pk_bf16_f32 v174, v174, v175
	global_store_short v240, v174, s[22:23] offset:256
	global_store_short_d16_hi v240, v174, s[22:23] offset:320
	v_mul_f32_e32 v176, v107, v221
	v_mul_f32_e32 v177, v123, v221
	v_cvt_pk_bf16_f32 v176, v176, v177
	global_store_short v240, v176, s[22:23] offset:384
	global_store_short_d16_hi v240, v176, s[22:23] offset:448
	v_add_u32_e32 v240, 0x24000, v241
	v_mul_f32_e32 v178, v10, v222
	v_mul_f32_e32 v179, v26, v222
	v_cvt_pk_bf16_f32 v178, v178, v179
	global_store_short v240, v178, s[22:23]
	global_store_short_d16_hi v240, v178, s[22:23] offset:64
	v_mul_f32_e32 v180, v42, v222
	v_mul_f32_e32 v181, v58, v222
	v_cvt_pk_bf16_f32 v180, v180, v181
	global_store_short v240, v180, s[22:23] offset:128
	global_store_short_d16_hi v240, v180, s[22:23] offset:192
	v_mul_f32_e32 v182, v74, v222
	v_mul_f32_e32 v183, v90, v222
	v_cvt_pk_bf16_f32 v182, v182, v183
	global_store_short v240, v182, s[22:23] offset:256
	global_store_short_d16_hi v240, v182, s[22:23] offset:320
	v_mul_f32_e32 v184, v108, v222
	v_mul_f32_e32 v185, v124, v222
	v_cvt_pk_bf16_f32 v184, v184, v185
	global_store_short v240, v184, s[22:23] offset:384
	global_store_short_d16_hi v240, v184, s[22:23] offset:448
	v_add_u32_e32 v240, 0x26000, v241
	v_mul_f32_e32 v186, v11, v223
	v_mul_f32_e32 v187, v27, v223
	v_cvt_pk_bf16_f32 v186, v186, v187
	global_store_short v240, v186, s[22:23]
	global_store_short_d16_hi v240, v186, s[22:23] offset:64
	v_mul_f32_e32 v188, v43, v223
	v_mul_f32_e32 v189, v59, v223
	v_cvt_pk_bf16_f32 v188, v188, v189
	global_store_short v240, v188, s[22:23] offset:128
	global_store_short_d16_hi v240, v188, s[22:23] offset:192
	v_mul_f32_e32 v190, v75, v223
	v_mul_f32_e32 v191, v91, v223
	v_cvt_pk_bf16_f32 v190, v190, v191
	global_store_short v240, v190, s[22:23] offset:256
	global_store_short_d16_hi v240, v190, s[22:23] offset:320
	v_mul_f32_e32 v192, v109, v223
	v_mul_f32_e32 v193, v125, v223
	v_cvt_pk_bf16_f32 v192, v192, v193
	global_store_short v240, v192, s[22:23] offset:384
	global_store_short_d16_hi v240, v192, s[22:23] offset:448
	v_add_u32_e32 v240, 0x30000, v241
	v_mul_f32_e32 v162, v12, v224
	v_mul_f32_e32 v163, v28, v224
	v_cvt_pk_bf16_f32 v162, v162, v163
	global_store_short v240, v162, s[22:23]
	global_store_short_d16_hi v240, v162, s[22:23] offset:64
	v_mul_f32_e32 v164, v44, v224
	v_mul_f32_e32 v165, v60, v224
	v_cvt_pk_bf16_f32 v164, v164, v165
	global_store_short v240, v164, s[22:23] offset:128
	global_store_short_d16_hi v240, v164, s[22:23] offset:192
	v_mul_f32_e32 v166, v76, v224
	v_mul_f32_e32 v167, v92, v224
	v_cvt_pk_bf16_f32 v166, v166, v167
	global_store_short v240, v166, s[22:23] offset:256
	global_store_short_d16_hi v240, v166, s[22:23] offset:320
	v_mul_f32_e32 v168, v110, v224
	v_mul_f32_e32 v169, v126, v224
	v_cvt_pk_bf16_f32 v168, v168, v169
	global_store_short v240, v168, s[22:23] offset:384
	global_store_short_d16_hi v240, v168, s[22:23] offset:448
	v_add_u32_e32 v240, 0x32000, v241
	v_mul_f32_e32 v170, v13, v225
	v_mul_f32_e32 v171, v29, v225
	v_cvt_pk_bf16_f32 v170, v170, v171
	global_store_short v240, v170, s[22:23]
	global_store_short_d16_hi v240, v170, s[22:23] offset:64
	v_mul_f32_e32 v172, v45, v225
	v_mul_f32_e32 v173, v61, v225
	v_cvt_pk_bf16_f32 v172, v172, v173
	global_store_short v240, v172, s[22:23] offset:128
	global_store_short_d16_hi v240, v172, s[22:23] offset:192
	v_mul_f32_e32 v174, v77, v225
	v_mul_f32_e32 v175, v93, v225
	v_cvt_pk_bf16_f32 v174, v174, v175
	global_store_short v240, v174, s[22:23] offset:256
	global_store_short_d16_hi v240, v174, s[22:23] offset:320
	v_mul_f32_e32 v176, v111, v225
	v_mul_f32_e32 v177, v127, v225
	v_cvt_pk_bf16_f32 v176, v176, v177
	global_store_short v240, v176, s[22:23] offset:384
	global_store_short_d16_hi v240, v176, s[22:23] offset:448
	v_add_u32_e32 v240, 0x34000, v241
	v_mul_f32_e32 v178, v14, v226
	v_mul_f32_e32 v179, v30, v226
	v_cvt_pk_bf16_f32 v178, v178, v179
	global_store_short v240, v178, s[22:23]
	global_store_short_d16_hi v240, v178, s[22:23] offset:64
	v_mul_f32_e32 v180, v46, v226
	v_mul_f32_e32 v181, v62, v226
	v_cvt_pk_bf16_f32 v180, v180, v181
	global_store_short v240, v180, s[22:23] offset:128
	global_store_short_d16_hi v240, v180, s[22:23] offset:192
	v_mul_f32_e32 v182, v78, v226
	v_mul_f32_e32 v183, v94, v226
	v_cvt_pk_bf16_f32 v182, v182, v183
	global_store_short v240, v182, s[22:23] offset:256
	global_store_short_d16_hi v240, v182, s[22:23] offset:320
	v_mul_f32_e32 v184, v112, v226
	v_mul_f32_e32 v185, v128, v226
	v_cvt_pk_bf16_f32 v184, v184, v185
	global_store_short v240, v184, s[22:23] offset:384
	global_store_short_d16_hi v240, v184, s[22:23] offset:448
	v_add_u32_e32 v240, 0x36000, v241
	v_mul_f32_e32 v186, v15, v227
	v_mul_f32_e32 v187, v31, v227
	v_cvt_pk_bf16_f32 v186, v186, v187
	global_store_short v240, v186, s[22:23]
	global_store_short_d16_hi v240, v186, s[22:23] offset:64
	v_mul_f32_e32 v188, v47, v227
	v_mul_f32_e32 v189, v63, v227
	v_cvt_pk_bf16_f32 v188, v188, v189
	global_store_short v240, v188, s[22:23] offset:128
	global_store_short_d16_hi v240, v188, s[22:23] offset:192
	v_mul_f32_e32 v190, v79, v227
	v_mul_f32_e32 v191, v95, v227
	v_cvt_pk_bf16_f32 v190, v190, v191
	global_store_short v240, v190, s[22:23] offset:256
	global_store_short_d16_hi v240, v190, s[22:23] offset:320
	v_mul_f32_e32 v192, v113, v227
	v_mul_f32_e32 v193, v129, v227
	v_cvt_pk_bf16_f32 v192, v192, v193
	global_store_short v240, v192, s[22:23] offset:384
	global_store_short_d16_hi v240, v192, s[22:23] offset:448
	s_waitcnt lgkmcnt(0)
	s_barrier
	s_brev_b32 s30, 64
	v_readlane_b32 s31, v254, 63
	s_movk_i32 s61, 0x1000
	s_mov_b64 s[6:7], 0
